# waves 1-7 warm L2 with the next GEMM phase's first weight tile while thread 0 waits in the group barrier
# speedup vs baseline: 1.0027x; 1.0027x over previous
; __device__ __forceinline__ int tid_now(int wave_s) { int l; asm volatile("v_mbcnt_lo_u32_b32 %0, -1, 0\n\tv_mbcnt_hi_u32_b32 %0, -1, %0" : "=v"(l)); return wave_s * 64 + l; }
; template <bool F16, class Sched, class Epi>
; __device__ __forceinline__ void gemm_phase(LAS unsigned char* lds, const Gemm g, const Sched& S, const Epi& E, int wave_s) {
;     const int tid = tid_now(wave_s);
;     const int wid = __builtin_amdgcn_readfirstlane(tid >> 6), lane = tid & 63, wr = wid >> 2, wc = wid & 3, fr = lane & 15, fq = lane >> 4;
;     const int K = g.K, nt = K / BK, lda = g.lda;
;     unsigned voffA[2], voffB[2];
; #pragma unroll
;     for (int i = 0; i < 2; ++i) { int R, C; stage_rc(tid * 16 + i * 8192, R, C); const int Rb = (R & ~31) + perm32(R & 31);
;         voffA[i] = (unsigned)(R * lda + C) * 2u; voffB[i] = (unsigned)(Rb * K + C) * 2u; }
;     const size_t kstep = (size_t)(BK * 2);
;     const size_t hstepA = (size_t)HALF * lda * 2, hstepB = (size_t)HALF * K * 2;
;     const size_t tstepA = 2 * hstepA, tstepB = 2 * hstepB;
;     const unsigned ldsw = (unsigned)wid * 1024u;
;     const int aoff = lds_byte(wr * 64 + fr, fq * 8), boff = lds_byte(wc * 32 + fr, fq * 8);
;     ...
;     Unit cur, nxt; int ui = 0;
;     if (!S.next(0, cur)) return;
;     f32x4 acc[2][2][4][2];
; #pragma unroll
;     for (int a = 0; a < 2; ++a)
; #pragma unroll
;         for (int b = 0; b < 2; ++b)
; #pragma unroll
;             for (int m = 0; m < 4; ++m)
; #pragma unroll
;                 for (int n = 0; n < 2; ++n) acc[a][b][m][n] = (f32x4){0.f, 0.f, 0.f, 0.f};
;     bf16x8 At[4][2], B0[2][2], B1[2][2];
;     const char* cA = (const char*)g.A + PG8_AOFF(cur); const char* cB = (const char*)g.Bt + (size_t)cur.pn * tstepB;
;     PG8_STAGE(PG8_SB(0, 0), cB, voffB); PG8_STAGE(PG8_SB(0, 1), cB + hstepB, voffB); PG8_STAGE(PG8_SA(0, 0), cA, voffA); PG8_STAGE(PG8_SA(0, 1), cA + hstepA, voffA);
;     if (wr == 1) PG8_BAR;
;     PG8_WAIT_V(2); PG8_BAR;
; __global__ void __launch_bounds__(NWAVES * 64, 2) fwd_megakernel(Args args_unused) {
;     ...
;             {
;                 ArgsP A = get_args();
;                 pg8::GroupOrder S; S.init(0, D / 256, GS, GC, GRP);
;                 pg8::Gemm g{WSP(WS_O), WSP(WS_WPOOL) + (size_t)j * D * 512, NTOK, D, 512, D, 1, 512};
;                 pg8::EpiResid E{XBCUR, SSQ(3 * i + 1)};
;                 pg8::gemm_phase<false>(lds, g, S, E, wave_s);
.LBB0_223:
	s_or_b64 exec, exec, s[2:3]
	s_cmp_eq_u32 s81, 0
	s_cbranch_scc1 .Lpf_skip_0
	s_load_dwordx2 vcc, s[78:79], 0xa0
	v_mbcnt_lo_u32_b32 v100, -1, 0
	v_mbcnt_hi_u32_b32 v100, -1, v100
	v_subrev_u32_e32 v100, s81, v100
	v_subrev_u32_e32 v100, 64, v100
	v_add_u32_e32 v103, 0x1c0, v100
	v_min_u32_e32 v103, 0x1ff, v103
	v_mov_b32_e32 v104, s75
	v_lshrrev_b32_e32 v104, 5, v104
	v_mov_b32_e32 v105, 0x200000
	v_mov_b32_e32 v101, s20
	v_lshrrev_b32_e32 v101, 1, v101
	v_mul_lo_u32 v105, v105, v101
	v_mov_b32_e32 v101, 0x40000
	v_mul_lo_u32 v104, v104, v101
	v_add_u32_e32 v104, v104, v105
	v_add_u32_e32 v104, 0x4000000, v104
	v_lshrrev_b32_e32 v101, 1, v100
	v_mov_b32_e32 v105, 0x400
	v_mul_lo_u32 v101, v101, v105
	v_and_b32_e32 v102, 1, v100
	v_lshl_add_u32 v101, v102, 7, v101
	v_add_u32_e32 v101, v101, v104
	v_lshrrev_b32_e32 v102, 1, v103
	v_mul_lo_u32 v102, v102, v105
	v_and_b32_e32 v103, 1, v103
	v_lshl_add_u32 v103, v103, 7, v102
	v_add_u32_e32 v103, v103, v104
	s_waitcnt lgkmcnt(0)
	global_load_dword v102, v101, vcc
	global_load_dword v104, v103, vcc
.Lpf_skip_0:
	s_mov_b64 s[0:1], s[78:79]
	s_mov_b32 s2, s75
	s_waitcnt lgkmcnt(0)
	s_barrier
	s_ashr_i32 s21, s2, 3
	s_mov_b32 s4, s75
	v_mbcnt_lo_u32_b32 v14, -1, 0
	v_mbcnt_hi_u32_b32 v14, -1, v14
	s_cmp_gt_u32 s21, 31
	v_add_u32_e32 v0, s80, v14
	s_nop 0
	v_readfirstlane_b32 s10, v0
	s_cbranch_scc1 .LBB0_243
	v_lshlrev_b32_e32 v1, 4, v0
	v_add_u32_e32 v2, 0x2000, v1
	v_ashrrev_i32_e32 v3, 31, v2
	v_lshrrev_b32_e32 v3, 22, v3
	v_add_u32_e32 v3, v2, v3
	v_ashrrev_i32_e32 v8, 10, v3
	v_mul_i32_i24_e32 v4, 0x400, v8
	v_sub_u32_e32 v2, v2, v4
	v_lshrrev_b32_e32 v4, 4, v2
	v_bitop3_b32 v2, v4, v2, 32 bitop3:0x6c
	v_ashrrev_i32_e32 v4, 31, v2
	v_lshrrev_b32_e32 v4, 26, v4
	v_add_u32_e32 v4, v2, v4
	v_ashrrev_i32_e32 v9, 6, v4
	v_and_b32_e32 v4, 0xc0, v4
	v_sub_u32_e32 v2, v2, v4
	v_ashrrev_i16_sdwa v2, v234, sext(v2) dst_sel:DWORD dst_unused:UNUSED_PAD src0_sel:DWORD src1_sel:BYTE_0
	v_lshlrev_b32_e32 v3, 5, v8
	v_bfe_i32 v10, v2, 0, 16
	v_lshlrev_b32_e32 v2, 3, v8
	v_and_b32_e32 v3, 32, v3
	v_and_b32_e32 v2, -16, v2
	s_load_dwordx2 s[2:3], s[0:1], 0xa0
	s_lshl_b32 s0, s4, 2
	v_add_u32_e32 v2, v9, v2
	v_and_b32_e32 v4, 3, v9
	s_mov_b32 s4, 0x3fffe0
	v_add_lshl_u32 v3, v3, v10, 1
	v_and_or_b32 v4, v2, s4, v4
	v_lshrrev_b32_e32 v5, 2, v2
	v_lshlrev_b32_e32 v6, 1, v2
	v_lshl_add_u32 v130, v2, 12, v3
	v_ashrrev_i32_e32 v2, 31, v0
	v_lshrrev_b32_e32 v2, 26, v2
	v_add_u32_e32 v2, v0, v2
	v_bfe_i32 v0, v0, 27, 1
	v_lshrrev_b32_e32 v0, 22, v0
	v_add_u32_e32 v0, v1, v0
	v_and_b32_e32 v0, 0xfffffc00, v0
	v_sub_u32_e32 v0, v1, v0
	v_lshrrev_b32_e32 v1, 4, v0
	v_bitop3_b32 v0, v1, v0, 32 bitop3:0x6c
	v_ashrrev_i32_e32 v1, 31, v0
	v_lshrrev_b32_e32 v1, 26, v1
	v_add_u32_e32 v1, v0, v1
	s_and_b32 s34, s0, 28
	v_ashrrev_i32_e32 v12, 6, v1
	v_and_b32_e32 v1, 0xc0, v1
	s_waitcnt lgkmcnt(0)
	s_add_u32 s35, s2, 0x20000000
	v_sub_u32_e32 v0, v0, v1
	s_addc_u32 s36, s3, 0
	s_lshl_b32 s0, s50, 21
	v_ashrrev_i32_e32 v11, 6, v2
	v_ashrrev_i16_sdwa v0, v234, sext(v0) dst_sel:DWORD dst_unused:UNUSED_PAD src0_sel:DWORD src1_sel:BYTE_0
	s_add_u32 s0, s2, s0
	v_bfe_i32 v13, v0, 0, 16
	v_lshlrev_b32_e32 v0, 3, v11
	s_addc_u32 s1, s3, 0
	v_and_b32_e32 v0, -16, v0
	s_add_u32 s37, s0, 0x4000000
	v_add_u32_e32 v0, v12, v0
	v_and_b32_e32 v1, 3, v12
	s_addc_u32 s38, s1, 0
	v_and_or_b32 v1, v0, s4, v1
	s_and_b32 s4, s21, 3
	s_ashr_i32 s0, s10, 6
	s_or_b32 s52, s34, s4
	s_lshl_b32 s5, s21, 7
	s_ashr_i32 s1, s10, 8
	s_lshl_b32 s39, s0, 10
	v_and_b32_e32 v5, 4, v5
	v_and_b32_e32 v6, 24, v6
	s_lshr_b32 s49, s21, 2
	s_lshl_b32 s4, s52, 20
	s_and_b32 s6, s5, 0xc00
	v_or3_b32 v4, v4, v5, v6
	s_add_u32 s7, s35, s4
	v_lshl_add_u32 v128, v4, 10, v3
	v_lshlrev_b32_e32 v2, 5, v11
	v_lshrrev_b32_e32 v3, 2, v0
	v_lshlrev_b32_e32 v4, 1, v0
	s_addc_u32 s8, s36, 0
	s_lshl_b32 s4, s49, 18
	v_and_b32_e32 v2, 32, v2
	v_and_b32_e32 v3, 4, v3
	v_and_b32_e32 v4, 24, v4
	s_add_u32 s28, s37, s4
	v_or3_b32 v1, v1, v3, v4
	v_add_lshl_u32 v2, v2, v13, 1
	s_addc_u32 s29, s38, 0
	s_add_i32 s41, s39, 0
	v_lshl_add_u32 v176, v1, 10, v2
	s_add_i32 m0, s41, 0x10000
	v_lshl_add_u32 v132, v0, 12, v2
	global_load_lds_dwordx4 v176, s[28:29]
	s_add_i32 m0, s41, 0x12000
	s_add_u32 s4, s28, 0x20000
	global_load_lds_dwordx4 v128, s[28:29]
	s_addc_u32 s5, s29, 0
	s_add_i32 m0, s41, 0x14000
	v_mov_b32_e32 v129, v177
	global_load_lds_dwordx4 v176, s[4:5]
	s_add_i32 m0, s41, 0x16000
	s_add_u32 s26, s7, s6
	s_addc_u32 s27, s8, 0
	s_add_i32 s42, s41, 0x2000
	global_load_lds_dwordx4 v128, s[4:5]
	s_mov_b32 m0, s41
	s_add_u32 s4, s26, 0x80000
	global_load_lds_dwordx4 v132, s[26:27]
	s_mov_b32 m0, s42
	s_addc_u32 s5, s27, 0
	s_add_i32 s43, s41, 0x4000
	global_load_lds_dwordx4 v130, s[26:27]
	s_mov_b32 m0, s43
	s_add_i32 s44, s41, 0x6000
	global_load_lds_dwordx4 v132, s[4:5]
	s_mov_b32 m0, s44
	v_mov_b32_e32 v133, v177
	global_load_lds_dwordx4 v130, s[4:5]
	v_mov_b32_e32 v131, v177
	s_cmp_eq_u32 s1, 1
	v_lshl_add_u64 v[6:7], s[28:29], 0, v[176:177]
	v_lshl_add_u64 v[4:5], s[28:29], 0, v[128:129]
	v_lshl_add_u64 v[0:1], s[26:27], 0, v[132:133]
	s_cselect_b64 s[4:5], -1, 0
	s_cmp_lg_u32 s1, 1
	v_lshl_add_u64 v[2:3], s[26:27], 0, v[130:131]
	s_cbranch_scc1 .LBB0_226
	s_barrier

; #define LAS __attribute__((address_space(3)))
;     __device__ void init(int M, int N, int G_, int c_) { asm volatile("" : "+s"(c_)); nM = M / BM; nN = N / BM; nwg = nM * nN; G = G_; c = c_; }
;     __device__ void init(int mode_, int nOther, int G_, int c_, int grp) { asm volatile("" : "+s"(c_)); mode = mode_; nwg = 4 * nOther; G = G_; c = c_; p0 = 4 * grp; }
; __device__ __forceinline__ ArgsP get_args() { ArgsP p = (ArgsP)__builtin_amdgcn_kernarg_segment_ptr(); asm volatile("" : "+s"(p)); return p; }
; #define XBCUR WSP((i & 1) ? WS_H2 : WS_H)
; #define GRP (blk_now() & 7)
; #define GC (blk_now() >> 3)
; __device__ __forceinline__ void xcd_barrier(const XcdBarrier& b, bool tid0) {
;     ...
;     __syncthreads();
; __global__ void __launch_bounds__(NWAVES * 64, 2) fwd_megakernel(Args args_unused) {
;     ...
;         {
;             ArgsP A = get_args();
;             pg8::GroupOrder S; S.init(0, 2 * DFF / 256, GS, GC, GRP);
;             pg8::Gemm g{XBCUR, WSP(WS_WGU) + (size_t)i * 2 * DFF * D, NTOK, 2 * DFF, D, D, 0, 0};
;             pg8::EpiGU E{WSP(WS_ACT), (const LAS float*)(lds + 131072)};
;             pg8::gemm_phase<true>(lds, g, S, E, wave_s);
.LBB0_295:
	s_or_b64 exec, exec, s[2:3]
	s_cmp_eq_u32 s81, 0
	s_cbranch_scc1 .Lpf_skip_2
	s_load_dwordx2 vcc, s[78:79], 0xa0
	v_mbcnt_lo_u32_b32 v100, -1, 0
	v_mbcnt_hi_u32_b32 v100, -1, v100
	v_subrev_u32_e32 v100, s81, v100
	v_subrev_u32_e32 v100, 64, v100
	v_add_u32_e32 v103, 0x1c0, v100
	v_min_u32_e32 v103, 0x1ff, v103
	v_mov_b32_e32 v104, s75
	v_lshrrev_b32_e32 v104, 5, v104
	v_mov_b32_e32 v105, 0x2c00000
	v_mul_lo_u32 v105, v105, s20
	v_mov_b32_e32 v101, 0x100000
	v_mul_lo_u32 v104, v104, v101
	v_add_u32_e32 v104, v104, v105
	v_add_u32_e32 v104, 0x4400000, v104
	v_lshrrev_b32_e32 v101, 1, v100
	v_mov_b32_e32 v105, 0x1000
	v_mul_lo_u32 v101, v101, v105
	v_and_b32_e32 v102, 1, v100
	v_lshl_add_u32 v101, v102, 7, v101
	v_add_u32_e32 v101, v101, v104
	v_lshrrev_b32_e32 v102, 1, v103
	v_mul_lo_u32 v102, v102, v105
	v_and_b32_e32 v103, 1, v103
	v_lshl_add_u32 v103, v103, 7, v102
	v_add_u32_e32 v103, v103, v104
	s_waitcnt lgkmcnt(0)
	global_load_dword v102, v101, vcc
	global_load_dword v104, v103, vcc
.Lpf_skip_2:
	s_mov_b64 s[0:1], 0
	s_waitcnt lgkmcnt(0)
	s_barrier

; __device__ __forceinline__ int tid_now(int wave_s) { int l; asm volatile("v_mbcnt_lo_u32_b32 %0, -1, 0\n\tv_mbcnt_hi_u32_b32 %0, -1, %0" : "=v"(l)); return wave_s * 64 + l; }
; template <bool F16, class Sched, class Epi>
; __device__ __forceinline__ void gemm_phase(LAS unsigned char* lds, const Gemm g, const Sched& S, const Epi& E, int wave_s) {
;     const int tid = tid_now(wave_s);
;     const int wid = __builtin_amdgcn_readfirstlane(tid >> 6), lane = tid & 63, wr = wid >> 2, wc = wid & 3, fr = lane & 15, fq = lane >> 4;
;     const int K = g.K, nt = K / BK, lda = g.lda;
;     unsigned voffA[2], voffB[2];
; #pragma unroll
;     for (int i = 0; i < 2; ++i) { int R, C; stage_rc(tid * 16 + i * 8192, R, C); const int Rb = (R & ~31) + perm32(R & 31);
;         voffA[i] = (unsigned)(R * lda + C) * 2u; voffB[i] = (unsigned)(Rb * K + C) * 2u; }
;     const size_t kstep = (size_t)(BK * 2);
;     const size_t hstepA = (size_t)HALF * lda * 2, hstepB = (size_t)HALF * K * 2;
;     const size_t tstepA = 2 * hstepA, tstepB = 2 * hstepB;
;     const unsigned ldsw = (unsigned)wid * 1024u;
;     const int aoff = lds_byte(wr * 64 + fr, fq * 8), boff = lds_byte(wc * 32 + fr, fq * 8);
;     ...
;     Unit cur, nxt; int ui = 0;
;     if (!S.next(0, cur)) return;
;     f32x4 acc[2][2][4][2];
; #pragma unroll
;     for (int a = 0; a < 2; ++a)
; #pragma unroll
;         for (int b = 0; b < 2; ++b)
; #pragma unroll
;             for (int m = 0; m < 4; ++m)
; #pragma unroll
;                 for (int n = 0; n < 2; ++n) acc[a][b][m][n] = (f32x4){0.f, 0.f, 0.f, 0.f};
;     bf16x8 At[4][2], B0[2][2], B1[2][2];
;     const char* cA = (const char*)g.A + PG8_AOFF(cur); const char* cB = (const char*)g.Bt + (size_t)cur.pn * tstepB;
;     PG8_STAGE(PG8_SB(0, 0), cB, voffB); PG8_STAGE(PG8_SB(0, 1), cB + hstepB, voffB); PG8_STAGE(PG8_SA(0, 0), cA, voffA); PG8_STAGE(PG8_SA(0, 1), cA + hstepA, voffA);
;     if (wr == 1) PG8_BAR;
;     PG8_WAIT_V(2); PG8_BAR;
; __global__ void __launch_bounds__(NWAVES * 64, 2) fwd_megakernel(Args args_unused) {
;     ...
;             {
;                 ArgsP A = get_args();
;                 pg8::GroupOrder S; S.init(0, D / 256, GS, GC, GRP);
;                 pg8::Gemm g{WSP(WS_O), WSP(WS_WO) + (size_t)j * D * D, NTOK, D, D, D, 0, 0};
;                 pg8::EpiResid E{XBCUR, SSQ(3 * i + 1)};
;                 pg8::gemm_phase<false>(lds, g, S, E, wave_s);
.LBB0_591:
	s_or_b64 exec, exec, s[2:3]
	s_cmp_eq_u32 s81, 0
	s_cbranch_scc1 .Lpf_skip_1
	s_load_dwordx2 vcc, s[78:79], 0xa0
	v_mbcnt_lo_u32_b32 v100, -1, 0
	v_mbcnt_hi_u32_b32 v100, -1, v100
	v_subrev_u32_e32 v100, s81, v100
	v_subrev_u32_e32 v100, 64, v100
	v_add_u32_e32 v103, 0x1c0, v100
	v_min_u32_e32 v103, 0x1ff, v103
	v_mov_b32_e32 v104, s75
	v_lshrrev_b32_e32 v104, 5, v104
	v_mov_b32_e32 v105, 0x800000
	v_mov_b32_e32 v101, s20
	v_lshrrev_b32_e32 v101, 1, v101
	v_mul_lo_u32 v105, v105, v101
	v_mov_b32_e32 v101, 0x100000
	v_mul_lo_u32 v104, v104, v101
	v_add_u32_e32 v104, v104, v105
	v_add_u32_e32 v104, 0x3000000, v104
	v_lshrrev_b32_e32 v101, 1, v100
	v_mov_b32_e32 v105, 0x1000
	v_mul_lo_u32 v101, v101, v105
	v_and_b32_e32 v102, 1, v100
	v_lshl_add_u32 v101, v102, 7, v101
	v_add_u32_e32 v101, v101, v104
	v_lshrrev_b32_e32 v102, 1, v103
	v_mul_lo_u32 v102, v102, v105
	v_and_b32_e32 v103, 1, v103
	v_lshl_add_u32 v103, v103, 7, v102
	v_add_u32_e32 v103, v103, v104
	s_waitcnt lgkmcnt(0)
	global_load_dword v102, v101, vcc
	global_load_dword v104, v103, vcc
.Lpf_skip_1:
	s_mov_b64 s[0:1], s[78:79]
	s_mov_b32 s2, s75
	s_waitcnt lgkmcnt(0)
	s_barrier
	s_ashr_i32 s21, s2, 3
	s_mov_b32 s4, s75
	v_mbcnt_lo_u32_b32 v14, -1, 0
	v_mbcnt_hi_u32_b32 v14, -1, v14
	s_cmp_gt_u32 s21, 31
	v_add_u32_e32 v0, s80, v14
	s_nop 0
	v_readfirstlane_b32 s14, v0
	s_cbranch_scc1 .LBB0_607
	v_lshlrev_b32_e32 v1, 4, v0
	v_add_u32_e32 v2, 0x2000, v1
	v_ashrrev_i32_e32 v3, 31, v2
	v_lshrrev_b32_e32 v3, 22, v3
	v_add_u32_e32 v3, v2, v3
	v_ashrrev_i32_e32 v8, 10, v3
	v_mul_i32_i24_e32 v4, 0x400, v8
	v_sub_u32_e32 v2, v2, v4
	v_lshrrev_b32_e32 v4, 4, v2
	v_bitop3_b32 v2, v4, v2, 32 bitop3:0x6c
	v_ashrrev_i32_e32 v4, 31, v2
	v_lshrrev_b32_e32 v4, 26, v4
	v_add_u32_e32 v4, v2, v4
	v_ashrrev_i32_e32 v9, 6, v4
	v_and_b32_e32 v4, 0xc0, v4
	v_sub_u32_e32 v2, v2, v4
	v_ashrrev_i16_sdwa v2, v234, sext(v2) dst_sel:DWORD dst_unused:UNUSED_PAD src0_sel:DWORD src1_sel:BYTE_0
	v_lshlrev_b32_e32 v3, 5, v8
	v_bfe_i32 v10, v2, 0, 16
	v_lshlrev_b32_e32 v2, 3, v8
	v_and_b32_e32 v3, 32, v3
	v_and_b32_e32 v2, -16, v2
	s_load_dwordx2 s[2:3], s[0:1], 0xa0
	s_lshl_b32 s0, s4, 2
	v_add_u32_e32 v2, v9, v2
	v_and_b32_e32 v4, 3, v9
	s_mov_b32 s4, 0xfffe0
	v_add_lshl_u32 v3, v3, v10, 1
	v_and_or_b32 v4, v2, s4, v4
	v_lshrrev_b32_e32 v5, 2, v2
	v_lshlrev_b32_e32 v6, 1, v2
	v_lshl_add_u32 v130, v2, 12, v3
	v_ashrrev_i32_e32 v2, 31, v0
	v_lshrrev_b32_e32 v2, 26, v2
	v_add_u32_e32 v2, v0, v2
	v_bfe_i32 v0, v0, 27, 1
	v_lshrrev_b32_e32 v0, 22, v0
	v_add_u32_e32 v0, v1, v0
	v_and_b32_e32 v0, 0xfffffc00, v0
	v_sub_u32_e32 v0, v1, v0
	v_lshrrev_b32_e32 v1, 4, v0
	v_bitop3_b32 v0, v1, v0, 32 bitop3:0x6c
	v_ashrrev_i32_e32 v1, 31, v0
	v_lshrrev_b32_e32 v1, 26, v1
	v_add_u32_e32 v1, v0, v1
	s_and_b32 s34, s0, 28
	v_ashrrev_i32_e32 v12, 6, v1
	v_and_b32_e32 v1, 0xc0, v1
	s_waitcnt lgkmcnt(0)
	s_add_u32 s35, s2, 0x20000000
	v_sub_u32_e32 v0, v0, v1
	s_addc_u32 s36, s3, 0
	s_lshl_b64 s[0:1], s[24:25], 1
	v_ashrrev_i32_e32 v11, 6, v2
	v_ashrrev_i16_sdwa v0, v234, sext(v0) dst_sel:DWORD dst_unused:UNUSED_PAD src0_sel:DWORD src1_sel:BYTE_0
	s_add_u32 s0, s2, s0
	v_bfe_i32 v13, v0, 0, 16
	v_lshlrev_b32_e32 v0, 3, v11
	s_addc_u32 s1, s3, s1
	v_and_b32_e32 v0, -16, v0
	s_add_u32 s37, s0, 0x3000000
	v_add_u32_e32 v0, v12, v0
	v_and_b32_e32 v1, 3, v12
	s_addc_u32 s38, s1, 0
	v_and_or_b32 v1, v0, s4, v1
	s_and_b32 s4, s21, 3
	s_ashr_i32 s0, s14, 6
	s_or_b32 s41, s34, s4
	s_ashr_i32 s1, s14, 8
	s_lshl_b32 s39, s0, 10
	v_and_b32_e32 v5, 4, v5
	v_and_b32_e32 v6, 24, v6
	s_lshr_b32 s42, s21, 2
	s_lshl_b32 s4, s41, 20
	v_or3_b32 v4, v4, v5, v6
	s_add_u32 s4, s35, s4
	v_lshl_add_u32 v128, v4, 12, v3
	v_lshlrev_b32_e32 v2, 5, v11
	v_lshrrev_b32_e32 v3, 2, v0
	v_lshlrev_b32_e32 v4, 1, v0
	s_addc_u32 s5, s36, 0
	s_lshl_b32 s6, s42, 20
	v_and_b32_e32 v2, 32, v2
	v_and_b32_e32 v3, 4, v3
	v_and_b32_e32 v4, 24, v4
	s_add_u32 s6, s37, s6
	v_or3_b32 v1, v1, v3, v4
	v_add_lshl_u32 v2, v2, v13, 1
	s_addc_u32 s7, s38, 0
	s_add_i32 s43, s39, 0
	v_lshl_add_u32 v176, v1, 12, v2
	s_add_i32 m0, s43, 0x10000
	v_lshl_add_u32 v132, v0, 12, v2
	global_load_lds_dwordx4 v176, s[6:7]
	s_add_i32 m0, s43, 0x12000
	s_add_u32 s8, s6, 0x80000
	global_load_lds_dwordx4 v128, s[6:7]
	s_addc_u32 s9, s7, 0
	s_add_i32 m0, s43, 0x14000
	s_add_i32 s44, s43, 0x2000
	global_load_lds_dwordx4 v176, s[8:9]
	s_add_i32 m0, s43, 0x16000
	v_mov_b32_e32 v129, v177
	global_load_lds_dwordx4 v128, s[8:9]
	s_mov_b32 m0, s43
	s_add_u32 s8, s4, 0x80000
	global_load_lds_dwordx4 v132, s[4:5]
	s_mov_b32 m0, s44
	s_addc_u32 s9, s5, 0
	s_add_i32 s45, s43, 0x4000
	global_load_lds_dwordx4 v130, s[4:5]
	s_mov_b32 m0, s45
	s_add_i32 s46, s43, 0x6000
	global_load_lds_dwordx4 v132, s[8:9]
	s_mov_b32 m0, s46
	v_mov_b32_e32 v133, v177
	global_load_lds_dwordx4 v130, s[8:9]
	v_mov_b32_e32 v131, v177
	s_cmp_eq_u32 s1, 1
	v_lshl_add_u64 v[6:7], s[6:7], 0, v[176:177]
	v_lshl_add_u64 v[4:5], s[6:7], 0, v[128:129]
	v_lshl_add_u64 v[0:1], s[4:5], 0, v[132:133]
	s_cselect_b64 s[8:9], -1, 0
	s_cmp_lg_u32 s1, 1
	v_lshl_add_u64 v[2:3], s[4:5], 0, v[130:131]
	s_cbranch_scc1 .LBB0_594
	s_barrier

; __device__ __forceinline__ void xcd_barrier(const XcdBarrier& b, bool tid0) {
;     ...
;     __syncthreads();
.Lpf_skip_3:
	s_waitcnt lgkmcnt(0)
	s_barrier

; #define GC (blk_now() >> 3)
; #define GROUP_BAR() do { ArgsP A_ = get_args(); XcdBarrier b_; b_.bar = (unsigned*)(A_->ws + WS_BAR) + 4096 * GRP; b_.x = xb_xcc_id(); b_.st = bar_st; b_.G = (unsigned)GS; xcd_barrier(b_, tid_now(wave_s) == 0); } while (0)
; #define CONV_DONE(n) do { ArgsP A_ = get_args(); if (tid_now(wave_s) == 0) (void)xb_add(CONV_WORD(n), 1u); } while (0)
; #define CONV_WAIT(n) do { ArgsP A_ = get_args(); if (tid_now(wave_s) == 0) { unsigned sp_ = 0u; while (xb_ld(CONV_WORD(n)) < (unsigned)(G / 2)) { __builtin_amdgcn_s_sleep(1); if (++sp_ > XB_SPIN_CAP) break; } \
;         __builtin_amdgcn_fence(__ATOMIC_ACQUIRE, "agent"); asm volatile("s_waitcnt vmcnt(0)" ::: "memory"); } __syncthreads(); } while (0)
; __global__ void __launch_bounds__(NWAVES * 64, 2) fwd_megakernel(Args args_unused) {
;     ...
;         GROUP_BAR();
;         if (i + 1 < DEPTH && GC >= GS / 2) CONV_DONE(i + 1);
;         if (i > 0) CONV_WAIT(i);
.LBB0_765:
	s_or_b64 exec, exec, s[2:3]
	s_cmp_eq_u32 s81, 0
	s_cbranch_scc1 .Lpf_skip_4
	s_load_dwordx2 vcc, s[78:79], 0xa0
	v_mbcnt_lo_u32_b32 v100, -1, 0
	v_mbcnt_hi_u32_b32 v100, -1, v100
	v_subrev_u32_e32 v100, s81, v100
	v_subrev_u32_e32 v100, 64, v100
	v_add_u32_e32 v103, 0x1c0, v100
	v_min_u32_e32 v103, 0x1ff, v103
	v_mov_b32_e32 v104, s75
	v_lshrrev_b32_e32 v104, 5, v104
	v_mov_b32_e32 v105, 0x1600000
	v_mul_lo_u32 v105, v105, s20
	v_mov_b32_e32 v101, 0x2c0000
	v_mul_lo_u32 v104, v104, v101
	v_add_u32_e32 v104, v104, v105
	v_add_u32_e32 v104, 0xf400000, v104
	v_lshrrev_b32_e32 v101, 1, v100
	v_mov_b32_e32 v105, 0x2c00
	v_mul_lo_u32 v101, v101, v105
	v_and_b32_e32 v102, 1, v100
	v_lshl_add_u32 v101, v102, 7, v101
	v_add_u32_e32 v101, v101, v104
	v_lshrrev_b32_e32 v102, 1, v103
	v_mul_lo_u32 v102, v102, v105
	v_and_b32_e32 v103, 1, v103
	v_lshl_add_u32 v103, v103, 7, v102
	v_add_u32_e32 v103, v103, v104
	s_waitcnt lgkmcnt(0)
	global_load_dword v102, v101, vcc
	global_load_dword v104, v103, vcc
.Lpf_skip_4:
	s_waitcnt lgkmcnt(0)
	v_cndmask_b32_e64 v0, 0, 1, s[6:7]
	v_cmp_ne_u32_e64 s[2:3], 1, v0
	s_andn2_b64 vcc, exec, s[6:7]
	s_barrier
	s_cbranch_vccnz .LBB0_771
	s_mov_b32 s0, s75
	s_ashr_i32 s0, s0, 3
	s_cmp_lt_i32 s0, s87
	s_cbranch_scc1 .LBB0_771
	s_mov_b64 s[6:7], s[78:79]
	v_mbcnt_lo_u32_b32 v0, -1, 0
	v_mbcnt_hi_u32_b32 v0, -1, v0
	s_nop 0
	v_cmp_eq_u32_e32 vcc, s81, v0
	s_and_saveexec_b64 s[0:1], vcc
	s_cbranch_execz .LBB0_770
	s_mov_b64 s[8:9], exec
	v_mbcnt_lo_u32_b32 v0, s8, 0
	v_mbcnt_hi_u32_b32 v0, s9, v0
	v_cmp_eq_u32_e32 vcc, 0, v0
	s_and_b64 s[10:11], exec, vcc
	s_mov_b64 exec, s[10:11]
	s_cbranch_execz .LBB0_770
	s_load_dwordx2 s[6:7], s[6:7], 0xa0
	v_readlane_b32 s10, v255, 27
	v_readlane_b32 s11, v255, 28
	s_lshl_b32 s50, s10, 6
	s_lshl_b64 s[10:11], s[50:51], 2
	s_waitcnt lgkmcnt(0)
	s_add_u32 s6, s6, s10
	s_addc_u32 s7, s7, s11
	s_bcnt1_i32_b64 s8, s[8:9]
	v_mov_b32_e32 v0, s8
	v_mov_b32_e32 v1, 0x26134000
	global_atomic_add v1, v0, s[6:7]

;     __device__ void init(int M, int N, int G_, int c_) { asm volatile("" : "+s"(c_)); nM = M / BM; nN = N / BM; nwg = nM * nN; G = G_; c = c_; }
;     __device__ void init(int mode_, int nOther, int G_, int c_, int grp) { asm volatile("" : "+s"(c_)); mode = mode_; nwg = 4 * nOther; G = G_; c = c_; p0 = 4 * grp; }
; __device__ __forceinline__ ArgsP get_args() { ArgsP p = (ArgsP)__builtin_amdgcn_kernarg_segment_ptr(); asm volatile("" : "+s"(p)); return p; }
; #define XBCUR WSP((i & 1) ? WS_H2 : WS_H)
; #define XBNXT WSP((i & 1) ? WS_H : WS_H2)
; #define GRP (blk_now() & 7)
; #define GC (blk_now() >> 3)
; #define GROUP_BAR() do { ArgsP A_ = get_args(); XcdBarrier b_; b_.bar = (unsigned*)(A_->ws + WS_BAR) + 4096 * GRP; b_.x = xb_xcc_id(); b_.st = bar_st; b_.G = (unsigned)GS; xcd_barrier(b_, tid_now(wave_s) == 0); } while (0)
; __global__ void __launch_bounds__(NWAVES * 64, 2) fwd_megakernel(Args args_unused) {
;     ...
;         GROUP_BAR();
;         if (i < DEPTH - 1) {
;             {
;                 ArgsP A = get_args();
;                 pg8::GroupOrder S; S.init(0, D / 256, GS, GC, GRP);
;                 pg8::Gemm g{XBCUR, WSP(WS_WPG) + (size_t)i * D * D, NTOK, D, D, D, 0, 0};
;                 pg8::EpiPle E{XBCUR, XBNXT, WSP(WS_PP), A->in[16] + i * D, SSQ(3 * i + 2), SSQ(3 * i + 3)};
;                 pg8::gemm_phase<true>(lds, g, S, E, wave_s);
.LBB0_859:
	s_or_b64 exec, exec, s[4:5]
	s_cmp_eq_u32 s81, 0
	s_cbranch_scc1 .Lpf_skip_5
	s_load_dwordx2 vcc, s[78:79], 0xa0
	v_mbcnt_lo_u32_b32 v100, -1, 0
	v_mbcnt_hi_u32_b32 v100, -1, v100
	v_subrev_u32_e32 v100, s81, v100
	v_subrev_u32_e32 v100, 64, v100
	v_add_u32_e32 v103, 0x1c0, v100
	v_min_u32_e32 v103, 0x1ff, v103
	v_mov_b32_e32 v104, s75
	v_lshrrev_b32_e32 v104, 5, v104
	v_mov_b32_e32 v105, 0x800000
	v_mul_lo_u32 v105, v105, s20
	v_mov_b32_e32 v101, 0x100000
	v_mul_lo_u32 v104, v104, v101
	v_add_u32_e32 v104, v104, v105
	v_add_u32_e32 v104, 0x14c00000, v104
	v_lshrrev_b32_e32 v101, 1, v100
	v_mov_b32_e32 v105, 0x1000
	v_mul_lo_u32 v101, v101, v105
	v_and_b32_e32 v102, 1, v100
	v_lshl_add_u32 v101, v102, 7, v101
	v_add_u32_e32 v101, v101, v104
	v_lshrrev_b32_e32 v102, 1, v103
	v_mul_lo_u32 v102, v102, v105
	v_and_b32_e32 v103, 1, v103
	v_lshl_add_u32 v103, v103, 7, v102
	v_add_u32_e32 v103, v103, v104
	s_waitcnt lgkmcnt(0)
	global_load_dword v102, v101, vcc
	global_load_dword v104, v103, vcc
.Lpf_skip_5:
	s_and_b64 vcc, exec, s[2:3]
	s_mov_b64 s[0:1], -1
	s_waitcnt lgkmcnt(0)
	s_barrier
	s_cbranch_vccnz .LBB0_985
	s_mov_b64 s[4:5], s[78:79]
	s_mov_b32 s0, s75
	s_ashr_i32 s36, s0, 3
	s_mov_b32 s1, s75
	v_mbcnt_lo_u32_b32 v8, -1, 0
	v_mbcnt_hi_u32_b32 v8, -1, v8
	s_cmp_gt_u32 s36, 31
	v_add_u32_e32 v0, s80, v8
	s_nop 0
	v_readfirstlane_b32 s0, v0
	s_cbranch_scc0 .LBB0_863
	s_mov_b64 s[0:1], -1
	s_and_b64 vcc, exec, s[16:17]
	s_mov_b32 s36, 0x8000
	s_cbranch_vccnz .LBB0_878
